# v28: v27 + P5 odd workgroups run units as (t0,PLE)(t1,PLE)(t0,gate)(t1,gate): desynchronises the heavy gate epilogues of the two grid halves
# speedup vs baseline: 1.0086x; 1.0004x over previous
;     __device__ bool next(int i, Unit& u) const {
;         const int it = (nseg == 2) ? (i >> 1) : i;
;         const long L = (long)it * G + c; if (L >= nwg) return false;
;         int wgid = (int)L; { const int q = nwg / NXCD, r = nwg % NXCD, xcd = wgid % NXCD, off = wgid / NXCD; wgid = (xcd < r ? xcd * (q + 1) : r * (q + 1) + (xcd - r) * q) + off; }
;         const int nig = WGM * nN, gid = wgid / nig, fm = gid * WGM, gsz = (nM - fm) < WGM ? (nM - fm) : WGM;
;         u.pm = fm + ((wgid % nig) % gsz); u.pn = (wgid % nig) / gsz; u.seg = (nseg == 2) ? (i & 1) : 0; u.ti = it; return true;
; template <class Epi, int AC0, int BC0, int NT0, int AC1, int BC1, int NT1>
; __device__ __forceinline__ void gemm_phase(LAS unsigned char* lds, const Gemm g, const StaticOrder& S, const Epi& E, int tid) {
;     ...
;         const bool has_next = S.next(ui + 1, nxt);
;         const char* nA = has_next ? PG8_APTR(nxt) : cA; const char* nB = has_next ? PG8_BPTR(nxt) : cB;
;         const int nt = NT0 + cur.seg * (NT1 - NT0);
.LBB0_985:
	s_add_i32 s41, s41, 1
	s_lshr_b32 s14, s41, 1
	s_bitcmp1_b32 s94, 0
	s_cbranch_scc0 .Lp5o_a
	s_and_b32 s14, s41, 1
	s_lshr_b32 s0, s41, 2
	s_lshl_b32 s0, s0, 1
	s_or_b32 s14, s14, s0
.Lp5o_a:
	s_mul_i32 s0, s14, s93
	s_mul_hi_i32 s1, s14, s93
	s_add_u32 s0, s0, s94
	s_addc_u32 s1, s1, s95
	v_cmp_ge_i64_e32 vcc, s[0:1], v[204:205]
	v_cmp_lt_i64_e64 s[4:5], s[0:1], v[204:205]
	s_cbranch_vccnz .LBB0_987
	s_ashr_i32 s1, s0, 31
	s_lshr_b32 s1, s1, 29
	s_add_i32 s1, s0, s1
	s_ashr_i32 s15, s1, 3
	s_and_b32 s1, s1, -8
	s_sub_i32 s0, s0, s1
	s_lshr_b32 s1, s0, 31
	s_add_i32 s1, s36, s1
	s_mul_i32 s0, s1, s0
	s_add_i32 s0, s0, s15
	s_ashr_i32 s1, s0, 31
	s_lshr_b32 s1, s1, 27
	s_add_i32 s1, s0, s1
	s_ashr_i32 s15, s1, 5
	s_lshl_b32 s15, s15, 3
	s_sub_i32 s22, s26, s15
	s_min_i32 s22, s22, 8
	s_abs_i32 s23, s22
	v_cvt_f32_u32_e32 v0, s23
	s_sub_i32 s25, 0, s23
	s_andn2_b32 s1, s1, 31
	s_sub_i32 s0, s0, s1
	v_rcp_iflag_f32_e32 v0, v0
	s_abs_i32 s1, s0
	s_xor_b32 s24, s0, s22
	s_ashr_i32 s24, s24, 31
	v_mul_f32_e32 v0, 0x4f7ffffe, v0
	v_cvt_u32_f32_e32 v0, v0
	s_mov_b32 s43, s14
	v_readfirstlane_b32 s33, v0
	s_mul_i32 s25, s25, s33
	s_mul_hi_u32 s25, s33, s25
	s_add_i32 s33, s33, s25
	s_mul_hi_u32 s25, s1, s33
	s_mul_i32 s33, s25, s23
	s_sub_i32 s1, s1, s33
	s_add_i32 s42, s25, 1
	s_sub_i32 s33, s1, s23
	s_cmp_ge_u32 s1, s23
	s_cselect_b32 s25, s42, s25
	s_cselect_b32 s1, s33, s1
	s_add_i32 s33, s25, 1
	s_cmp_ge_u32 s1, s23
	s_cselect_b32 s1, s33, s25
	s_xor_b32 s1, s1, s24
	s_sub_i32 s42, s1, s24
	s_mul_i32 s1, s42, s22
	s_sub_i32 s0, s0, s1
	s_add_i32 s45, s0, s15
	s_and_b32 s44, s41, 1
	s_bitcmp1_b32 s94, 0
	s_cbranch_scc0 .Lp5o_b
	s_bfe_u32 s44, s41, 0x10001
.Lp5o_b:
.LBB0_987:
	s_nop 0
	v_cndmask_b32_e64 v0, 0, 1, s[4:5]
	v_cmp_ne_u32_e64 s[0:1], 1, v0
	s_andn2_b64 vcc, exec, s[4:5]
	s_mov_b64 s[4:5], s[18:19]
	s_cbranch_vccnz .LBB0_989
	s_lshl_b32 s4, s44, 10
	s_sub_i32 s4, 0x400, s4
	s_ashr_i32 s5, s4, 31
	s_mul_i32 s15, s45, 0xa0000
	s_lshl_b64 s[4:5], s[4:5], 1
	s_mul_hi_i32 s14, s45, 0xa0000
	s_add_u32 s15, s82, s15
	s_addc_u32 s14, s83, s14
	s_add_u32 s4, s15, s4
	s_addc_u32 s5, s14, s5
